# final-norm fusion: partial sums published with write-through stores instead of an L2 writeback per workgroup
# speedup vs baseline: 1.0019x; 1.0019x over previous
;     __device__ __forceinline__ void emit(int row, int pn, int col0, float* v) const {
;     ...
;         case K_WO: case K_DN: {
;             const size_t o = ((size_t)grp * TG + row) * D + col0;
;             const f32x4 a0 = ldg<f32x4>(xi + o), a1 = ldg<f32x4>(xi + o + 4);
;             f32x4 r0, r1; r0.x = a0.x + v[0]; r0.y = a0.y + v[1]; r0.z = a0.z + v[2]; r0.w = a0.w + v[3]; r1.x = a1.x + v[4]; r1.y = a1.y + v[5]; r1.z = a1.z + v[6]; r1.w = a1.w + v[7];
;             stg<f32x4>(xo + o, r0); stg<f32x4>(xo + o + 4, r1);
;         } break;
;     __device__ __forceinline__ void operator()(const f32x4 (&acc)[2][2][4][2], const pg8::Unit& u, int wr, int wc, int fr, int fq) const {
;     ...
;         for (int ai = 0; ai < 2; ++ai)
; #pragma unroll
;             for (int m = 0; m < 4; ++m)
; #pragma unroll
;                 for (int bj = 0; bj < 2; ++bj) {
;                     float v[8]; const f32x4 v0 = acc[ai][bj][m][0], v1 = acc[ai][bj][m][1];
;                     v[0] = v0.x; v[1] = v0.y; v[2] = v0.z; v[3] = v0.w; v[4] = v1.x; v[5] = v1.y; v[6] = v1.z; v[7] = v1.w;
;                     emit(row0 + ai * 128 + m * 16, u.pn, colb + bj * 128, v);
.Lfn_epi:
	v_lshl_add_u32 v202, s43, 8, v186
	s_lshl_b32 s98, s42, 8
	v_or_b32_e32 v203, s98, v188
	v_lshl_add_u32 v242, v202, 10, v203
	v_add_u32_e32 v242, s0, v242
	v_lshlrev_b32_e32 v242, 2, v242
	v_mov_b32_e32 v182, v242
	v_add_u32_e32 v183, 0x10000, v242
	v_add_u32_e32 v184, 0x20000, v242
	v_add_u32_e32 v185, 0x30000, v242
	v_add_u32_e32 v190, 0x80000, v242
	v_add_u32_e32 v191, 0x90000, v242
	v_add_u32_e32 v200, 0xa0000, v242
	v_add_u32_e32 v201, 0xb0000, v242
	global_load_dwordx4 v[210:213], v182, s[74:75]
	global_load_dwordx4 v[214:217], v182, s[74:75] offset:16
	global_load_dwordx4 v[218:221], v182, s[74:75] offset:512
	global_load_dwordx4 v[222:225], v182, s[74:75] offset:528
	global_load_dwordx4 v[226:229], v183, s[74:75]
	global_load_dwordx4 v[230:233], v183, s[74:75] offset:16
	global_load_dwordx4 v[234:237], v183, s[74:75] offset:512
	global_load_dwordx4 v[238:241], v183, s[74:75] offset:528
	global_load_dwordx4 v[132:135], v184, s[74:75]
	global_load_dwordx4 v[136:139], v184, s[74:75] offset:16
	global_load_dwordx4 v[140:143], v184, s[74:75] offset:512
	global_load_dwordx4 v[144:147], v184, s[74:75] offset:528
	global_load_dwordx4 v[148:151], v185, s[74:75]
	global_load_dwordx4 v[152:155], v185, s[74:75] offset:16
	global_load_dwordx4 v[156:159], v185, s[74:75] offset:512
	global_load_dwordx4 v[160:163], v185, s[74:75] offset:528
	s_waitcnt vmcnt(8)
	v_pk_add_f32 v[128:129], v[128:129], v[210:211]
	v_pk_add_f32 v[130:131], v[130:131], v[212:213]
	v_pk_add_f32 v[124:125], v[124:125], v[214:215]
	v_pk_add_f32 v[126:127], v[126:127], v[216:217]
	v_pk_add_f32 v[120:121], v[120:121], v[218:219]
	v_pk_add_f32 v[122:123], v[122:123], v[220:221]
	v_pk_add_f32 v[116:117], v[116:117], v[222:223]
	v_pk_add_f32 v[118:119], v[118:119], v[224:225]
	v_pk_add_f32 v[112:113], v[112:113], v[226:227]
	v_pk_add_f32 v[114:115], v[114:115], v[228:229]
	v_pk_add_f32 v[108:109], v[108:109], v[230:231]
	v_pk_add_f32 v[110:111], v[110:111], v[232:233]
	v_pk_add_f32 v[104:105], v[104:105], v[234:235]
	v_pk_add_f32 v[106:107], v[106:107], v[236:237]
	v_pk_add_f32 v[100:101], v[100:101], v[238:239]
	v_pk_add_f32 v[102:103], v[102:103], v[240:241]
	global_load_dwordx4 v[210:213], v190, s[74:75]
	global_load_dwordx4 v[214:217], v190, s[74:75] offset:16
	global_load_dwordx4 v[218:221], v190, s[74:75] offset:512
	global_load_dwordx4 v[222:225], v190, s[74:75] offset:528
	global_load_dwordx4 v[226:229], v191, s[74:75]
	global_load_dwordx4 v[230:233], v191, s[74:75] offset:16
	global_load_dwordx4 v[234:237], v191, s[74:75] offset:512
	global_load_dwordx4 v[238:241], v191, s[74:75] offset:528
	s_waitcnt vmcnt(8)
	v_pk_add_f32 v[96:97], v[96:97], v[132:133]
	v_pk_add_f32 v[98:99], v[98:99], v[134:135]
	v_pk_add_f32 v[92:93], v[92:93], v[136:137]
	v_pk_add_f32 v[94:95], v[94:95], v[138:139]
	v_pk_add_f32 v[88:89], v[88:89], v[140:141]
	v_pk_add_f32 v[90:91], v[90:91], v[142:143]
	v_pk_add_f32 v[84:85], v[84:85], v[144:145]
	v_pk_add_f32 v[86:87], v[86:87], v[146:147]
	v_pk_add_f32 v[80:81], v[80:81], v[148:149]
	v_pk_add_f32 v[82:83], v[82:83], v[150:151]
	v_pk_add_f32 v[76:77], v[76:77], v[152:153]
	v_pk_add_f32 v[78:79], v[78:79], v[154:155]
	v_pk_add_f32 v[72:73], v[72:73], v[156:157]
	v_pk_add_f32 v[74:75], v[74:75], v[158:159]
	v_pk_add_f32 v[68:69], v[68:69], v[160:161]
	v_pk_add_f32 v[70:71], v[70:71], v[162:163]
	global_load_dwordx4 v[132:135], v200, s[74:75]
	global_load_dwordx4 v[136:139], v200, s[74:75] offset:16
	global_load_dwordx4 v[140:143], v200, s[74:75] offset:512
	global_load_dwordx4 v[144:147], v200, s[74:75] offset:528
	global_load_dwordx4 v[148:151], v201, s[74:75]
	global_load_dwordx4 v[152:155], v201, s[74:75] offset:16
	global_load_dwordx4 v[156:159], v201, s[74:75] offset:512
	global_load_dwordx4 v[160:163], v201, s[74:75] offset:528
	s_waitcnt vmcnt(8)
	v_pk_add_f32 v[64:65], v[64:65], v[210:211]
	v_pk_add_f32 v[66:67], v[66:67], v[212:213]
	v_pk_add_f32 v[60:61], v[60:61], v[214:215]
	v_pk_add_f32 v[62:63], v[62:63], v[216:217]
	v_pk_add_f32 v[56:57], v[56:57], v[218:219]
	v_pk_add_f32 v[58:59], v[58:59], v[220:221]
	v_pk_add_f32 v[52:53], v[52:53], v[222:223]
	v_pk_add_f32 v[54:55], v[54:55], v[224:225]
	v_pk_add_f32 v[48:49], v[48:49], v[226:227]
	v_pk_add_f32 v[50:51], v[50:51], v[228:229]
	v_pk_add_f32 v[44:45], v[44:45], v[230:231]
	v_pk_add_f32 v[46:47], v[46:47], v[232:233]
	v_pk_add_f32 v[40:41], v[40:41], v[234:235]
	v_pk_add_f32 v[42:43], v[42:43], v[236:237]
	v_pk_add_f32 v[36:37], v[36:37], v[238:239]
	v_pk_add_f32 v[38:39], v[38:39], v[240:241]
	s_waitcnt vmcnt(0)
; __device__ __forceinline__ void rmsnorm_rows_f32(float* x, const float* gain, int nrows, int gw, int ngw, int lane) {
;     ...
;         f32x4* xr = (f32x4*)(x + (size_t)r * D) + lane; f32x4 v[4]; float s = 0.f;
; #pragma unroll
;         for (int j = 0; j < 4; ++j) { v[j] = xr[64 * j]; s += (v[j].x * v[j].x + v[j].y * v[j].y) + (v[j].z * v[j].z + v[j].w * v[j].w); }
;         const float rs = rsqrtf(wave_sum(s) * (1.f / D) + 1e-6f);
	v_pk_add_f32 v[32:33], v[32:33], v[132:133]
	v_pk_add_f32 v[34:35], v[34:35], v[134:135]
	v_pk_add_f32 v[28:29], v[28:29], v[136:137]
	v_pk_add_f32 v[30:31], v[30:31], v[138:139]
	v_pk_add_f32 v[24:25], v[24:25], v[140:141]
	v_pk_add_f32 v[26:27], v[26:27], v[142:143]
	v_pk_add_f32 v[20:21], v[20:21], v[144:145]
	v_pk_add_f32 v[22:23], v[22:23], v[146:147]
	v_pk_add_f32 v[16:17], v[16:17], v[148:149]
	v_pk_add_f32 v[18:19], v[18:19], v[150:151]
	v_pk_add_f32 v[12:13], v[12:13], v[152:153]
	v_pk_add_f32 v[14:15], v[14:15], v[154:155]
	v_pk_add_f32 v[8:9], v[8:9], v[156:157]
	v_pk_add_f32 v[10:11], v[10:11], v[158:159]
	v_pk_add_f32 v[4:5], v[4:5], v[160:161]
	v_pk_add_f32 v[6:7], v[6:7], v[162:163]
	v_pk_mul_f32 v[210:211], v[116:117], v[116:117]
	v_pk_fma_f32 v[210:211], v[118:119], v[118:119], v[210:211]
	v_pk_fma_f32 v[210:211], v[120:121], v[120:121], v[210:211]
	v_pk_fma_f32 v[210:211], v[122:123], v[122:123], v[210:211]
	v_pk_fma_f32 v[210:211], v[124:125], v[124:125], v[210:211]
	v_pk_fma_f32 v[210:211], v[126:127], v[126:127], v[210:211]
	v_pk_fma_f32 v[210:211], v[128:129], v[128:129], v[210:211]
	v_pk_fma_f32 v[210:211], v[130:131], v[130:131], v[210:211]
	v_pk_mul_f32 v[212:213], v[100:101], v[100:101]
	v_pk_fma_f32 v[212:213], v[102:103], v[102:103], v[212:213]
	v_pk_fma_f32 v[212:213], v[104:105], v[104:105], v[212:213]
	v_pk_fma_f32 v[212:213], v[106:107], v[106:107], v[212:213]
	v_pk_fma_f32 v[212:213], v[108:109], v[108:109], v[212:213]
	v_pk_fma_f32 v[212:213], v[110:111], v[110:111], v[212:213]
	v_pk_fma_f32 v[212:213], v[112:113], v[112:113], v[212:213]
	v_pk_fma_f32 v[212:213], v[114:115], v[114:115], v[212:213]
	v_pk_mul_f32 v[214:215], v[84:85], v[84:85]
	v_pk_fma_f32 v[214:215], v[86:87], v[86:87], v[214:215]
	v_pk_fma_f32 v[214:215], v[88:89], v[88:89], v[214:215]
	v_pk_fma_f32 v[214:215], v[90:91], v[90:91], v[214:215]
	v_pk_fma_f32 v[214:215], v[92:93], v[92:93], v[214:215]
	v_pk_fma_f32 v[214:215], v[94:95], v[94:95], v[214:215]
	v_pk_fma_f32 v[214:215], v[96:97], v[96:97], v[214:215]
	v_pk_fma_f32 v[214:215], v[98:99], v[98:99], v[214:215]
	v_pk_mul_f32 v[216:217], v[68:69], v[68:69]
	v_pk_fma_f32 v[216:217], v[70:71], v[70:71], v[216:217]
	v_pk_fma_f32 v[216:217], v[72:73], v[72:73], v[216:217]
	v_pk_fma_f32 v[216:217], v[74:75], v[74:75], v[216:217]
	v_pk_fma_f32 v[216:217], v[76:77], v[76:77], v[216:217]
	v_pk_fma_f32 v[216:217], v[78:79], v[78:79], v[216:217]
	v_pk_fma_f32 v[216:217], v[80:81], v[80:81], v[216:217]
	v_pk_fma_f32 v[216:217], v[82:83], v[82:83], v[216:217]
	v_pk_mul_f32 v[218:219], v[52:53], v[52:53]
	v_pk_fma_f32 v[218:219], v[54:55], v[54:55], v[218:219]
	v_pk_fma_f32 v[218:219], v[56:57], v[56:57], v[218:219]
	v_pk_fma_f32 v[218:219], v[58:59], v[58:59], v[218:219]
	v_pk_fma_f32 v[218:219], v[60:61], v[60:61], v[218:219]
	v_pk_fma_f32 v[218:219], v[62:63], v[62:63], v[218:219]
	v_pk_fma_f32 v[218:219], v[64:65], v[64:65], v[218:219]
	v_pk_fma_f32 v[218:219], v[66:67], v[66:67], v[218:219]
	v_pk_mul_f32 v[220:221], v[36:37], v[36:37]
	v_pk_fma_f32 v[220:221], v[38:39], v[38:39], v[220:221]
	v_pk_fma_f32 v[220:221], v[40:41], v[40:41], v[220:221]
	v_pk_fma_f32 v[220:221], v[42:43], v[42:43], v[220:221]
	v_pk_fma_f32 v[220:221], v[44:45], v[44:45], v[220:221]
	v_pk_fma_f32 v[220:221], v[46:47], v[46:47], v[220:221]
	v_pk_fma_f32 v[220:221], v[48:49], v[48:49], v[220:221]
	v_pk_fma_f32 v[220:221], v[50:51], v[50:51], v[220:221]
	v_pk_mul_f32 v[222:223], v[20:21], v[20:21]
	v_pk_fma_f32 v[222:223], v[22:23], v[22:23], v[222:223]
	v_pk_fma_f32 v[222:223], v[24:25], v[24:25], v[222:223]
	v_pk_fma_f32 v[222:223], v[26:27], v[26:27], v[222:223]
	v_pk_fma_f32 v[222:223], v[28:29], v[28:29], v[222:223]
	v_pk_fma_f32 v[222:223], v[30:31], v[30:31], v[222:223]
	v_pk_fma_f32 v[222:223], v[32:33], v[32:33], v[222:223]
	v_pk_fma_f32 v[222:223], v[34:35], v[34:35], v[222:223]
	v_pk_mul_f32 v[224:225], v[4:5], v[4:5]
	v_pk_fma_f32 v[224:225], v[6:7], v[6:7], v[224:225]
	v_pk_fma_f32 v[224:225], v[8:9], v[8:9], v[224:225]
	v_pk_fma_f32 v[224:225], v[10:11], v[10:11], v[224:225]
	v_pk_fma_f32 v[224:225], v[12:13], v[12:13], v[224:225]
	v_pk_fma_f32 v[224:225], v[14:15], v[14:15], v[224:225]
	v_pk_fma_f32 v[224:225], v[16:17], v[16:17], v[224:225]
	v_pk_fma_f32 v[224:225], v[18:19], v[18:19], v[224:225]
	v_add_f32_e32 v210, v210, v211
	v_add_f32_e32 v212, v212, v213
	v_add_f32_e32 v214, v214, v215
	v_add_f32_e32 v216, v216, v217
	v_add_f32_e32 v218, v218, v219
	v_add_f32_e32 v220, v220, v221
	v_add_f32_e32 v222, v222, v223
	v_add_f32_e32 v224, v224, v225
	v_lshrrev_b32_e32 v243, 4, v192
	v_and_b32_e32 v243, 15, v243
	v_lshlrev_b32_e32 v243, 2, v243
	v_lshl_add_u32 v243, v186, 6, v243
	v_add_u32_e32 v243, 0x20000, v243
	ds_write_b32 v243, v210
	ds_write_b32 v243, v212 offset:1024
	ds_write_b32 v243, v214 offset:2048
	ds_write_b32 v243, v216 offset:3072
	ds_write_b32 v243, v218 offset:8192
	ds_write_b32 v243, v220 offset:9216
	ds_write_b32 v243, v222 offset:10240
	ds_write_b32 v243, v224 offset:11264
	v_mov_b32_e32 v132, 0x25950
	ds_read_b64 v[132:133], v132
	s_waitcnt lgkmcnt(0)
	s_barrier
	v_readfirstlane_b32 s98, v132
	v_readfirstlane_b32 s99, v133
	v_readfirstlane_b32 s100, v192
	s_add_u32 s98, s98, 0x40000
	s_addc_u32 s99, s99, 0
	s_cmpk_gt_u32 s100, 0xff
	s_cbranch_scc1 .Lfn_nopart
	v_lshlrev_b32_e32 v0, 6, v192
	v_add_u32_e32 v0, 0x20000, v0
	ds_read_b128 v[226:229], v0
	ds_read_b128 v[230:233], v0 offset:16
	ds_read_b128 v[234:237], v0 offset:32
	ds_read_b128 v[238:241], v0 offset:48
	s_lshl_b32 s100, s42, 14
	s_lshl_b32 s101, s43, 8
	s_add_i32 s100, s100, s101
	v_add_u32_e32 v0, s100, v192
	v_lshlrev_b32_e32 v0, 2, v0
	s_waitcnt lgkmcnt(0)
	v_add_f32_e32 v226, v226, v227
	v_add_f32_e32 v226, v226, v228
	v_add_f32_e32 v226, v226, v229
	v_add_f32_e32 v226, v226, v230
	v_add_f32_e32 v226, v226, v231
	v_add_f32_e32 v226, v226, v232
	v_add_f32_e32 v226, v226, v233
	v_add_f32_e32 v226, v226, v234
	v_add_f32_e32 v226, v226, v235
	v_add_f32_e32 v226, v226, v236
	v_add_f32_e32 v226, v226, v237
	v_add_f32_e32 v226, v226, v238
	v_add_f32_e32 v226, v226, v239
	v_add_f32_e32 v226, v226, v240
	v_add_f32_e32 v226, v226, v241
	global_store_dword v0, v226, s[98:99] sc1
.Lfn_nopart:
	s_waitcnt vmcnt(0)
	s_barrier
	v_readfirstlane_b32 s100, v192
	s_cmp_lg_u32 s100, 0
	s_cbranch_scc1 .Lfn_bw
	v_readlane_b32 s100, v255, 12
	s_lshr_b32 s100, s100, 2
	s_add_i32 s100, s100, 16
	s_lshl_b32 s100, s100, 2
	v_mov_b32_e32 v0, s100
	v_lshl_add_u64 v[134:135], v[132:133], 0, v[0:1]
	s_mov_b64 exec, 1
	flat_atomic_add v[134:135], v194
	s_mov_b64 exec, -1
	s_mov_b32 s101, 0

; __device__ __forceinline__ void rmsnorm_rows_f32(float* x, const float* gain, int nrows, int gw, int ngw, int lane) {
;     ...
;         f32x4* xr = (f32x4*)(x + (size_t)r * D) + lane; f32x4 v[4]; float s = 0.f;
; #pragma unroll
;         for (int j = 0; j < 4; ++j) { v[j] = xr[64 * j]; s += (v[j].x * v[j].x + v[j].y * v[j].y) + (v[j].z * v[j].z + v[j].w * v[j].w); }
;         const float rs = rsqrtf(wave_sum(s) * (1.f / D) + 1e-6f);
; #pragma unroll
;         for (int j = 0; j < 4; ++j) xr[64 * j] = v[j] * rs * gv[j];
.Lfn_bw:
	s_barrier
	v_lshlrev_b32_e32 v136, 2, v202
	v_add_u32_e32 v137, 0x10000, v136
	v_add_u32_e32 v138, 0x20000, v136
	v_add_u32_e32 v139, 0x30000, v136
	global_load_dword v210, v136, s[98:99] sc1
	global_load_dword v211, v137, s[98:99] sc1
	global_load_dword v212, v138, s[98:99] sc1
	global_load_dword v213, v139, s[98:99] sc1
	global_load_dword v214, v136, s[98:99] offset:64 sc1
	global_load_dword v215, v137, s[98:99] offset:64 sc1
	global_load_dword v216, v138, s[98:99] offset:64 sc1
	global_load_dword v217, v139, s[98:99] offset:64 sc1
	global_load_dword v218, v136, s[98:99] offset:128 sc1
	global_load_dword v219, v137, s[98:99] offset:128 sc1
	global_load_dword v220, v138, s[98:99] offset:128 sc1
	global_load_dword v221, v139, s[98:99] offset:128 sc1
	global_load_dword v222, v136, s[98:99] offset:192 sc1
	global_load_dword v223, v137, s[98:99] offset:192 sc1
	global_load_dword v224, v138, s[98:99] offset:192 sc1
	global_load_dword v225, v139, s[98:99] offset:192 sc1
	global_load_dword v226, v136, s[98:99] offset:512 sc1
	global_load_dword v227, v137, s[98:99] offset:512 sc1
	global_load_dword v228, v138, s[98:99] offset:512 sc1
	global_load_dword v229, v139, s[98:99] offset:512 sc1
	global_load_dword v230, v136, s[98:99] offset:576 sc1
	global_load_dword v231, v137, s[98:99] offset:576 sc1
	global_load_dword v232, v138, s[98:99] offset:576 sc1
	global_load_dword v233, v139, s[98:99] offset:576 sc1
	global_load_dword v234, v136, s[98:99] offset:640 sc1
	global_load_dword v235, v137, s[98:99] offset:640 sc1
	global_load_dword v236, v138, s[98:99] offset:640 sc1
	global_load_dword v237, v139, s[98:99] offset:640 sc1
	global_load_dword v238, v136, s[98:99] offset:704 sc1
	global_load_dword v239, v137, s[98:99] offset:704 sc1
	global_load_dword v240, v138, s[98:99] offset:704 sc1
	global_load_dword v241, v139, s[98:99] offset:704 sc1
	v_mov_b32_e32 v0, 0x25940
	ds_read_b64 v[140:141], v0
	v_lshlrev_b32_e32 v0, 2, v203
	v_mov_b32_e32 v142, 0x358637bd
	s_waitcnt lgkmcnt(0)
	v_readfirstlane_b32 s100, v140
	v_readfirstlane_b32 s101, v141
	s_nop 4
	global_load_dwordx4 v[144:147], v0, s[100:101]
	global_load_dwordx4 v[148:151], v0, s[100:101] offset:16
	global_load_dwordx4 v[152:155], v0, s[100:101] offset:512
	global_load_dwordx4 v[156:159], v0, s[100:101] offset:528
	s_waitcnt vmcnt(0)
	v_add_f32_e32 v210, v210, v211
	v_add_f32_e32 v210, v210, v212
	v_add_f32_e32 v210, v210, v213
	v_fmamk_f32 v210, v210, 0x3a800000, v142
	v_add_f32_e32 v214, v214, v215
	v_add_f32_e32 v214, v214, v216
	v_add_f32_e32 v214, v214, v217
	v_fmamk_f32 v214, v214, 0x3a800000, v142
	v_add_f32_e32 v218, v218, v219
	v_add_f32_e32 v218, v218, v220
	v_add_f32_e32 v218, v218, v221
	v_fmamk_f32 v218, v218, 0x3a800000, v142
	v_add_f32_e32 v222, v222, v223
	v_add_f32_e32 v222, v222, v224
	v_add_f32_e32 v222, v222, v225
	v_fmamk_f32 v222, v222, 0x3a800000, v142
	v_add_f32_e32 v226, v226, v227
	v_add_f32_e32 v226, v226, v228
	v_add_f32_e32 v226, v226, v229
	v_fmamk_f32 v226, v226, 0x3a800000, v142
	v_add_f32_e32 v230, v230, v231
	v_add_f32_e32 v230, v230, v232
	v_add_f32_e32 v230, v230, v233
	v_fmamk_f32 v230, v230, 0x3a800000, v142
	v_add_f32_e32 v234, v234, v235
	v_add_f32_e32 v234, v234, v236
	v_add_f32_e32 v234, v234, v237
	v_fmamk_f32 v234, v234, 0x3a800000, v142
	v_add_f32_e32 v238, v238, v239
	v_add_f32_e32 v238, v238, v240
	v_add_f32_e32 v238, v238, v241
	v_fmamk_f32 v238, v238, 0x3a800000, v142
	v_rsq_f32_e32 v210, v210
	v_rsq_f32_e32 v214, v214
	v_rsq_f32_e32 v218, v218
	v_rsq_f32_e32 v222, v222
	v_rsq_f32_e32 v226, v226
	v_rsq_f32_e32 v230, v230
	v_rsq_f32_e32 v234, v234
	v_rsq_f32_e32 v238, v238
	s_nop 0
	v_pk_mul_f32 v[128:129], v[128:129], v[210:211] op_sel_hi:[1,0]
	v_pk_mul_f32 v[130:131], v[130:131], v[210:211] op_sel_hi:[1,0]
	v_pk_mul_f32 v[124:125], v[124:125], v[210:211] op_sel_hi:[1,0]
	v_pk_mul_f32 v[126:127], v[126:127], v[210:211] op_sel_hi:[1,0]
	v_pk_mul_f32 v[128:129], v[144:145], v[128:129]
	v_pk_mul_f32 v[130:131], v[146:147], v[130:131]
	v_pk_mul_f32 v[124:125], v[148:149], v[124:125]
	v_pk_mul_f32 v[126:127], v[150:151], v[126:127]
	global_store_dwordx4 v182, v[128:131], s[66:67]
	global_store_dwordx4 v182, v[124:127], s[66:67] offset:16
	v_pk_mul_f32 v[120:121], v[120:121], v[210:211] op_sel_hi:[1,0]
	v_pk_mul_f32 v[122:123], v[122:123], v[210:211] op_sel_hi:[1,0]
	v_pk_mul_f32 v[116:117], v[116:117], v[210:211] op_sel_hi:[1,0]
	v_pk_mul_f32 v[118:119], v[118:119], v[210:211] op_sel_hi:[1,0]
	v_pk_mul_f32 v[120:121], v[152:153], v[120:121]
	v_pk_mul_f32 v[122:123], v[154:155], v[122:123]
	v_pk_mul_f32 v[116:117], v[156:157], v[116:117]
	v_pk_mul_f32 v[118:119], v[158:159], v[118:119]
	global_store_dwordx4 v182, v[120:123], s[66:67] offset:512
	global_store_dwordx4 v182, v[116:119], s[66:67] offset:528
	v_pk_mul_f32 v[112:113], v[112:113], v[214:215] op_sel_hi:[1,0]
	v_pk_mul_f32 v[114:115], v[114:115], v[214:215] op_sel_hi:[1,0]
	v_pk_mul_f32 v[108:109], v[108:109], v[214:215] op_sel_hi:[1,0]
	v_pk_mul_f32 v[110:111], v[110:111], v[214:215] op_sel_hi:[1,0]
	v_pk_mul_f32 v[112:113], v[144:145], v[112:113]
	v_pk_mul_f32 v[114:115], v[146:147], v[114:115]
	v_pk_mul_f32 v[108:109], v[148:149], v[108:109]
	v_pk_mul_f32 v[110:111], v[150:151], v[110:111]
	global_store_dwordx4 v183, v[112:115], s[66:67]
	global_store_dwordx4 v183, v[108:111], s[66:67] offset:16
	v_pk_mul_f32 v[104:105], v[104:105], v[214:215] op_sel_hi:[1,0]
	v_pk_mul_f32 v[106:107], v[106:107], v[214:215] op_sel_hi:[1,0]
	v_pk_mul_f32 v[100:101], v[100:101], v[214:215] op_sel_hi:[1,0]
	v_pk_mul_f32 v[102:103], v[102:103], v[214:215] op_sel_hi:[1,0]
	v_pk_mul_f32 v[104:105], v[152:153], v[104:105]
; __device__ __forceinline__ void rmsnorm_rows_f32(float* x, const float* gain, int nrows, int gw, int ngw, int lane) {
;     ...
; #pragma unroll
;         for (int j = 0; j < 4; ++j) xr[64 * j] = v[j] * rs * gv[j];
	v_pk_mul_f32 v[106:107], v[154:155], v[106:107]
	v_pk_mul_f32 v[100:101], v[156:157], v[100:101]
	v_pk_mul_f32 v[102:103], v[158:159], v[102:103]
	global_store_dwordx4 v183, v[104:107], s[66:67] offset:512
	global_store_dwordx4 v183, v[100:103], s[66:67] offset:528
	v_pk_mul_f32 v[96:97], v[96:97], v[218:219] op_sel_hi:[1,0]
	v_pk_mul_f32 v[98:99], v[98:99], v[218:219] op_sel_hi:[1,0]
	v_pk_mul_f32 v[92:93], v[92:93], v[218:219] op_sel_hi:[1,0]
	v_pk_mul_f32 v[94:95], v[94:95], v[218:219] op_sel_hi:[1,0]
	v_pk_mul_f32 v[96:97], v[144:145], v[96:97]
	v_pk_mul_f32 v[98:99], v[146:147], v[98:99]
	v_pk_mul_f32 v[92:93], v[148:149], v[92:93]
	v_pk_mul_f32 v[94:95], v[150:151], v[94:95]
	global_store_dwordx4 v184, v[96:99], s[66:67]
	global_store_dwordx4 v184, v[92:95], s[66:67] offset:16
	v_pk_mul_f32 v[88:89], v[88:89], v[218:219] op_sel_hi:[1,0]
	v_pk_mul_f32 v[90:91], v[90:91], v[218:219] op_sel_hi:[1,0]
	v_pk_mul_f32 v[84:85], v[84:85], v[218:219] op_sel_hi:[1,0]
	v_pk_mul_f32 v[86:87], v[86:87], v[218:219] op_sel_hi:[1,0]
	v_pk_mul_f32 v[88:89], v[152:153], v[88:89]
	v_pk_mul_f32 v[90:91], v[154:155], v[90:91]
	v_pk_mul_f32 v[84:85], v[156:157], v[84:85]
	v_pk_mul_f32 v[86:87], v[158:159], v[86:87]
	global_store_dwordx4 v184, v[88:91], s[66:67] offset:512
	global_store_dwordx4 v184, v[84:87], s[66:67] offset:528
	v_pk_mul_f32 v[80:81], v[80:81], v[222:223] op_sel_hi:[1,0]
	v_pk_mul_f32 v[82:83], v[82:83], v[222:223] op_sel_hi:[1,0]
	v_pk_mul_f32 v[76:77], v[76:77], v[222:223] op_sel_hi:[1,0]
	v_pk_mul_f32 v[78:79], v[78:79], v[222:223] op_sel_hi:[1,0]
	v_pk_mul_f32 v[80:81], v[144:145], v[80:81]
	v_pk_mul_f32 v[82:83], v[146:147], v[82:83]
	v_pk_mul_f32 v[76:77], v[148:149], v[76:77]
	v_pk_mul_f32 v[78:79], v[150:151], v[78:79]
	global_store_dwordx4 v185, v[80:83], s[66:67]
	global_store_dwordx4 v185, v[76:79], s[66:67] offset:16
	v_pk_mul_f32 v[72:73], v[72:73], v[222:223] op_sel_hi:[1,0]
	v_pk_mul_f32 v[74:75], v[74:75], v[222:223] op_sel_hi:[1,0]
	v_pk_mul_f32 v[68:69], v[68:69], v[222:223] op_sel_hi:[1,0]
	v_pk_mul_f32 v[70:71], v[70:71], v[222:223] op_sel_hi:[1,0]
	v_pk_mul_f32 v[72:73], v[152:153], v[72:73]
	v_pk_mul_f32 v[74:75], v[154:155], v[74:75]
	v_pk_mul_f32 v[68:69], v[156:157], v[68:69]
	v_pk_mul_f32 v[70:71], v[158:159], v[70:71]
	global_store_dwordx4 v185, v[72:75], s[66:67] offset:512
	global_store_dwordx4 v185, v[68:71], s[66:67] offset:528
	v_pk_mul_f32 v[64:65], v[64:65], v[226:227] op_sel_hi:[1,0]
	v_pk_mul_f32 v[66:67], v[66:67], v[226:227] op_sel_hi:[1,0]
	v_pk_mul_f32 v[60:61], v[60:61], v[226:227] op_sel_hi:[1,0]
	v_pk_mul_f32 v[62:63], v[62:63], v[226:227] op_sel_hi:[1,0]
	v_pk_mul_f32 v[64:65], v[144:145], v[64:65]
	v_pk_mul_f32 v[66:67], v[146:147], v[66:67]
	v_pk_mul_f32 v[60:61], v[148:149], v[60:61]
	v_pk_mul_f32 v[62:63], v[150:151], v[62:63]
	global_store_dwordx4 v190, v[64:67], s[66:67]
	global_store_dwordx4 v190, v[60:63], s[66:67] offset:16
	v_pk_mul_f32 v[56:57], v[56:57], v[226:227] op_sel_hi:[1,0]
	v_pk_mul_f32 v[58:59], v[58:59], v[226:227] op_sel_hi:[1,0]
	v_pk_mul_f32 v[52:53], v[52:53], v[226:227] op_sel_hi:[1,0]
	v_pk_mul_f32 v[54:55], v[54:55], v[226:227] op_sel_hi:[1,0]
	v_pk_mul_f32 v[56:57], v[152:153], v[56:57]
	v_pk_mul_f32 v[58:59], v[154:155], v[58:59]
	v_pk_mul_f32 v[52:53], v[156:157], v[52:53]
	v_pk_mul_f32 v[54:55], v[158:159], v[54:55]
	global_store_dwordx4 v190, v[56:59], s[66:67] offset:512
	global_store_dwordx4 v190, v[52:55], s[66:67] offset:528
	v_pk_mul_f32 v[48:49], v[48:49], v[230:231] op_sel_hi:[1,0]
	v_pk_mul_f32 v[50:51], v[50:51], v[230:231] op_sel_hi:[1,0]
	v_pk_mul_f32 v[44:45], v[44:45], v[230:231] op_sel_hi:[1,0]
	v_pk_mul_f32 v[46:47], v[46:47], v[230:231] op_sel_hi:[1,0]
	v_pk_mul_f32 v[48:49], v[144:145], v[48:49]
	v_pk_mul_f32 v[50:51], v[146:147], v[50:51]
	v_pk_mul_f32 v[44:45], v[148:149], v[44:45]
	v_pk_mul_f32 v[46:47], v[150:151], v[46:47]
	global_store_dwordx4 v191, v[48:51], s[66:67]
	global_store_dwordx4 v191, v[44:47], s[66:67] offset:16
	v_pk_mul_f32 v[40:41], v[40:41], v[230:231] op_sel_hi:[1,0]
	v_pk_mul_f32 v[42:43], v[42:43], v[230:231] op_sel_hi:[1,0]
	v_pk_mul_f32 v[36:37], v[36:37], v[230:231] op_sel_hi:[1,0]
	v_pk_mul_f32 v[38:39], v[38:39], v[230:231] op_sel_hi:[1,0]
	v_pk_mul_f32 v[40:41], v[152:153], v[40:41]
	v_pk_mul_f32 v[42:43], v[154:155], v[42:43]
	v_pk_mul_f32 v[36:37], v[156:157], v[36:37]
	v_pk_mul_f32 v[38:39], v[158:159], v[38:39]
	global_store_dwordx4 v191, v[40:43], s[66:67] offset:512
	global_store_dwordx4 v191, v[36:39], s[66:67] offset:528
	v_pk_mul_f32 v[32:33], v[32:33], v[234:235] op_sel_hi:[1,0]
	v_pk_mul_f32 v[34:35], v[34:35], v[234:235] op_sel_hi:[1,0]
	v_pk_mul_f32 v[28:29], v[28:29], v[234:235] op_sel_hi:[1,0]
	v_pk_mul_f32 v[30:31], v[30:31], v[234:235] op_sel_hi:[1,0]
	v_pk_mul_f32 v[32:33], v[144:145], v[32:33]
	v_pk_mul_f32 v[34:35], v[146:147], v[34:35]
	v_pk_mul_f32 v[28:29], v[148:149], v[28:29]
	v_pk_mul_f32 v[30:31], v[150:151], v[30:31]
	global_store_dwordx4 v200, v[32:35], s[66:67]
	global_store_dwordx4 v200, v[28:31], s[66:67] offset:16
	v_pk_mul_f32 v[24:25], v[24:25], v[234:235] op_sel_hi:[1,0]
	v_pk_mul_f32 v[26:27], v[26:27], v[234:235] op_sel_hi:[1,0]
	v_pk_mul_f32 v[20:21], v[20:21], v[234:235] op_sel_hi:[1,0]
	v_pk_mul_f32 v[22:23], v[22:23], v[234:235] op_sel_hi:[1,0]
	v_pk_mul_f32 v[24:25], v[152:153], v[24:25]
	v_pk_mul_f32 v[26:27], v[154:155], v[26:27]
	v_pk_mul_f32 v[20:21], v[156:157], v[20:21]
	v_pk_mul_f32 v[22:23], v[158:159], v[22:23]
	global_store_dwordx4 v200, v[24:27], s[66:67] offset:512
	global_store_dwordx4 v200, v[20:23], s[66:67] offset:528
	v_pk_mul_f32 v[16:17], v[16:17], v[238:239] op_sel_hi:[1,0]
	v_pk_mul_f32 v[18:19], v[18:19], v[238:239] op_sel_hi:[1,0]
	v_pk_mul_f32 v[12:13], v[12:13], v[238:239] op_sel_hi:[1,0]
	v_pk_mul_f32 v[14:15], v[14:15], v[238:239] op_sel_hi:[1,0]
	v_pk_mul_f32 v[16:17], v[144:145], v[16:17]
	v_pk_mul_f32 v[18:19], v[146:147], v[18:19]
	v_pk_mul_f32 v[12:13], v[148:149], v[12:13]
	v_pk_mul_f32 v[14:15], v[150:151], v[14:15]
	global_store_dwordx4 v201, v[16:19], s[66:67]
	global_store_dwordx4 v201, v[12:15], s[66:67] offset:16
	v_pk_mul_f32 v[8:9], v[8:9], v[238:239] op_sel_hi:[1,0]
	v_pk_mul_f32 v[10:11], v[10:11], v[238:239] op_sel_hi:[1,0]
	v_pk_mul_f32 v[4:5], v[4:5], v[238:239] op_sel_hi:[1,0]
	v_pk_mul_f32 v[6:7], v[6:7], v[238:239] op_sel_hi:[1,0]
	v_pk_mul_f32 v[8:9], v[152:153], v[8:9]
	v_pk_mul_f32 v[10:11], v[154:155], v[10:11]
	v_pk_mul_f32 v[4:5], v[156:157], v[4:5]
	v_pk_mul_f32 v[6:7], v[158:159], v[6:7]
	global_store_dwordx4 v201, v[8:11], s[66:67] offset:512
	global_store_dwordx4 v201, v[4:7], s[66:67] offset:528
	s_branch .LBB0_1375
